# mixer chunk loop: bf16 packing of probabilities with v_cvt_pk_bf16_f32 (same RNE as the integer trick), no-op v_bfi removed
# speedup vs baseline: 1.2177x; 1.0009x over previous
; #define LAS __attribute__((address_space(3)))
; template <int DH, bool SOFTMAX, bool PREFETCH, class Spec>
; __device__ __forceinline__ void wave_attn(const Spec& sp, int nch, LAS bf16* vl, int lane, f32x4 (&oacc)[DH / 16], float& m_run, float& l_run) {
;     ...
;         for (int c = 0; c < nch; ++c) {
;             bf16x8 kf[2][KS];
; #pragma unroll
;             for (int kt = 0; kt < 2; ++kt)
; #pragma unroll
;                 for (int ks = 0; ks < KS; ++ks) kf[kt][ks] = kn[kt][ks];
; #pragma unroll
;             for (int r = 0; r < NP; ++r) { const int p = lane + 64 * r, key = p / PPR, pc = p % PPR; *(LAS v4u*)(vl + key * P + pc * 8) = vn[r]; }
;             if (c + 1 < nch) WA_LOAD(c + 1);
;             f32x4 st[2];
; #pragma unroll
;             for (int kt = 0; kt < 2; ++kt) { st[kt] = (f32x4){0.f, 0.f, 0.f, 0.f};
; #pragma unroll
;                 for (int ks = 0; ks < KS; ++ks) st[kt] = __builtin_amdgcn_mfma_f32_16x16x32_bf16(kf[kt][ks], qf[ks], st[kt], 0, 0, 0); }
;             float pv[8];
; #pragma unroll
;             for (int kt = 0; kt < 2; ++kt)
; #pragma unroll
;                 for (int j = 0; j < 4; ++j) pv[kt * 4 + j] = sp.score(st[kt][j], i, 32 * c + 16 * kt + 4 * g + j);
;             if constexpr (SOFTMAX) {
;                 float cm = pv[0];
; #pragma unroll
;                 for (int r = 1; r < 8; ++r) cm = fmaxf(cm, pv[r]);
;                 cm = fmaxf(cm, __shfl_xor(cm, 16)); cm = fmaxf(cm, __shfl_xor(cm, 32));
;                 const float mn = fmaxf(m_run, cm), sc = exp2f(m_run - mn);
;                 float ls = 0.f;
; #pragma unroll
;                 for (int r = 0; r < 8; ++r) { pv[r] = exp2f(pv[r] - mn); ls += pv[r]; }
;                 ls += __shfl_xor(ls, 16); ls += __shfl_xor(ls, 32);
;                 l_run = l_run * sc + ls; m_run = mn;
; #pragma unroll
;                 for (int dt = 0; dt < DT; ++dt) oacc[dt] = oacc[dt] * sc;
.LBB0_323:
	s_waitcnt vmcnt(4)
	v_mov_b64_e32 v[170:171], v[34:35]
	v_mov_b64_e32 v[162:163], v[26:27]
	v_mov_b64_e32 v[168:169], v[32:33]
	v_add_u32_e32 v32, s10, v88
	v_mov_b64_e32 v[160:161], v[24:25]
	v_subrev_u32_e32 v24, 32, v32
	v_mov_b64_e32 v[158:159], v[30:31]
	v_lshlrev_b32_e32 v24, s2, v24
	v_mov_b64_e32 v[156:157], v[28:29]
	s_waitcnt vmcnt(3)
	ds_write_b128 v122, v[40:43]
	s_waitcnt vmcnt(2)
	ds_write_b128 v123, v[44:47]
	s_waitcnt vmcnt(1)
	ds_write_b128 v124, v[48:51]
	s_waitcnt vmcnt(0)
	ds_write_b128 v125, v[52:55]
	v_add_u32_e32 v24, s18, v24
	v_add_lshl_u32 v32, v32, -16, s2
	v_add_u32_e32 v40, s10, v121
	v_med3_i32 v24, v24, 0, v187
	v_add_u32_e32 v32, s18, v32
	v_lshlrev_b32_e32 v40, s2, v40
	v_add_u32_e32 v44, s10, v120
	v_mov_b32_e32 v173, v136
	v_mul_u32_u24_e32 v136, 0x1c00, v24
	v_med3_i32 v32, v32, 0, v187
	v_add_u32_e32 v40, s18, v40
	v_lshlrev_b32_e32 v44, s2, v44
	v_add_u32_e32 v48, s10, v119
	v_mov_b64_e32 v[166:167], v[38:39]
	v_lshl_add_u64 v[24:25], v[74:75], 0, v[136:137]
	v_mul_u32_u24_e32 v136, 0x1c00, v32
	v_med3_i32 v40, v40, 0, v187
	v_add_u32_e32 v44, s18, v44
	v_lshlrev_b32_e32 v48, s2, v48
	v_add_u32_e32 v52, s10, v118
	v_mov_b64_e32 v[164:165], v[36:37]
	v_lshl_add_u64 v[32:33], v[74:75], 0, v[136:137]
	v_mul_u32_u24_e32 v136, 0x1c00, v40
	v_med3_i32 v44, v44, 0, v187
	v_add_u32_e32 v48, s18, v48
	v_lshlrev_b32_e32 v52, s2, v52
	v_lshl_add_u64 v[40:41], v[76:77], 0, v[136:137]
	v_mul_u32_u24_e32 v136, 0x1c00, v44
	v_med3_i32 v48, v48, 0, v187
	v_add_u32_e32 v52, s18, v52
	v_mfma_f32_16x16x32_bf16 v[156:159], v[156:159], v[16:19], 0
	v_lshl_add_u64 v[44:45], v[78:79], 0, v[136:137]
	v_mul_u32_u24_e32 v136, 0x1c00, v48
	v_med3_i32 v52, v52, 0, v187
	v_lshl_add_u64 v[48:49], v[80:81], 0, v[136:137]
	v_mul_u32_u24_e32 v136, 0x1c00, v52
	v_lshl_add_u64 v[52:53], v[82:83], 0, v[136:137]
	v_mov_b32_e32 v172, v70
	v_mfma_f32_16x16x32_bf16 v[156:159], v[160:163], v[20:23], v[156:159]
	v_mfma_f32_16x16x32_bf16 v[160:163], v[164:167], v[16:19], 0
	v_mfma_f32_16x16x32_bf16 v[160:163], v[168:171], v[20:23], v[160:163]
	v_add_u32_e32 v166, s10, v117
	global_load_dwordx4 v[28:31], v[24:25], off
	s_nop 0
	global_load_dwordx4 v[24:27], v[24:25], off offset:64
	global_load_dwordx4 v[36:39], v[32:33], off
	s_nop 0
	global_load_dwordx4 v[32:35], v[32:33], off offset:64
	global_load_dwordx4 v[40:43], v[40:41], off
	global_load_dwordx4 v[44:47], v[44:45], off
	global_load_dwordx4 v[48:51], v[48:49], off
	v_cvt_f32_i32_e32 v190, v166
	v_add_f32_e32 v200, 0xc2800000, v190
	v_add_f32_e32 v201, 0xc27c0000, v190
	v_add_f32_e32 v202, 0xc2780000, v190
	v_add_f32_e32 v203, 0xc2740000, v190
	v_add_f32_e32 v204, 0xc2400000, v190
	v_add_f32_e32 v205, 0xc23c0000, v190
	v_add_f32_e32 v206, 0xc2380000, v190
	v_add_f32_e32 v207, 0xc2340000, v190
	v_med3_f32 v208, v200, v194, v195
	v_med3_f32 v209, v201, v194, v195
	v_med3_f32 v210, v202, v194, v195
	v_med3_f32 v211, v203, v194, v195
	v_med3_f32 v212, v204, v194, v195
	v_med3_f32 v213, v205, v194, v195
	v_med3_f32 v214, v206, v194, v195
	v_med3_f32 v215, v207, v194, v195
	v_mul_f32_e32 v216, 0x3e38aa3b, v156
	v_mul_f32_e32 v217, 0x3e38aa3b, v157
	v_mul_f32_e32 v218, 0x3e38aa3b, v158
	v_mul_f32_e32 v219, 0x3e38aa3b, v159
	v_mul_f32_e32 v220, 0x3e38aa3b, v160
	v_mul_f32_e32 v221, 0x3e38aa3b, v161
	v_mul_f32_e32 v222, 0x3e38aa3b, v162
	v_mul_f32_e32 v223, 0x3e38aa3b, v163
	v_fma_f32 v216, |v200|, v196, v216
	v_fma_f32 v217, |v201|, v196, v217
	v_fma_f32 v218, |v202|, v196, v218
	v_fma_f32 v219, |v203|, v196, v219
	v_fma_f32 v220, |v204|, v196, v220
	v_fma_f32 v221, |v205|, v196, v221
	v_fma_f32 v222, |v206|, v196, v222
	v_fma_f32 v223, |v207|, v196, v223
	v_cmp_eq_f32_e64 vcc, v208, v200
	v_cmp_eq_f32_e64 s[0:1], v209, v201
	s_nop 0
	v_cndmask_b32_e64 v164, v188, v216, vcc
	v_cmp_eq_f32_e64 vcc, v210, v202
	v_cndmask_b32_e64 v165, v188, v217, s[0:1]
	v_cmp_eq_f32_e64 s[0:1], v211, v203
	v_cndmask_b32_e64 v158, v188, v218, vcc
	v_cmp_eq_f32_e64 vcc, v212, v204
	v_cndmask_b32_e64 v159, v188, v219, s[0:1]
	v_cmp_eq_f32_e64 s[0:1], v213, v205
	v_cndmask_b32_e64 v160, v188, v220, vcc
	v_cmp_eq_f32_e64 vcc, v214, v206
	v_cndmask_b32_e64 v161, v188, v221, s[0:1]
	v_cmp_eq_f32_e64 s[0:1], v215, v207
	v_cndmask_b32_e64 v162, v188, v222, vcc
	v_max_f32_e32 v136, v164, v165
	v_cndmask_b32_e64 v70, v188, v223, s[0:1]
	v_max3_f32 v136, v136, v158, v159
	v_max3_f32 v136, v136, v160, v161
	v_max3_f32 v136, v136, v162, v70
	ds_bpermute_b32 v141, v96, v136
	global_load_dwordx4 v[52:55], v[52:53], off
	s_add_i32 s10, s10, 32
	s_cmpk_lg_i32 s10, 0x80
	s_waitcnt lgkmcnt(0)
	v_max_f32_e32 v141, v141, v141
	v_max_f32_e32 v136, v136, v141
	ds_bpermute_b32 v141, v97, v136
	s_waitcnt lgkmcnt(0)
	v_max3_f32 v136, v173, v136, v141
	v_sub_f32_e32 v156, v164, v136
	v_sub_f32_e32 v158, v158, v136
	v_sub_f32_e32 v159, v159, v136
	v_exp_f32_e32 v156, v156
	v_sub_f32_e32 v160, v160, v136
	v_sub_f32_e32 v161, v161, v136
	v_mov_b32_e32 v157, v156
	v_sub_f32_e32 v156, v165, v136
	v_sub_f32_e32 v162, v162, v136
	v_sub_f32_e32 v70, v70, v136
	v_exp_f32_e32 v156, v156
	v_sub_f32_e32 v141, v173, v136
	v_exp_f32_e32 v158, v158
	v_mov_b32_e32 v163, v156
	v_exp_f32_e32 v159, v159
	v_add_f32_e32 v156, v157, v163
	v_exp_f32_e32 v160, v160
	v_add_f32_e32 v156, v158, v156
	v_exp_f32_e32 v161, v161
	v_add_f32_e32 v156, v159, v156
	v_exp_f32_e32 v162, v162
	v_add_f32_e32 v156, v160, v156
	v_exp_f32_e32 v70, v70
	v_add_f32_e32 v156, v161, v156
	v_add_f32_e32 v156, v162, v156
	v_mov_b32_e32 v164, v70
	v_add_f32_e32 v70, v164, v156
	v_exp_f32_e32 v141, v141
	s_nop 0
	v_mov_b32_e32 v156, v141
	ds_bpermute_b32 v141, v96, v70
	v_pk_mul_f32 v[2:3], v[2:3], v[156:157] op_sel_hi:[1,0]
	v_pk_mul_f32 v[0:1], v[0:1], v[156:157] op_sel_hi:[1,0]
	v_pk_mul_f32 v[6:7], v[6:7], v[156:157] op_sel_hi:[1,0]
	v_pk_mul_f32 v[4:5], v[4:5], v[156:157] op_sel_hi:[1,0]
	s_waitcnt lgkmcnt(0)
; __device__ __forceinline__ unsigned pk2(float lo, float hi) { return f2bf(lo) | (f2bf(hi) << 16); }
; template <int DH, bool SOFTMAX, bool PREFETCH, class Spec>
; __device__ __forceinline__ void wave_attn(const Spec& sp, int nch, LAS bf16* vl, int lane, f32x4 (&oacc)[DH / 16], float& m_run, float& l_run) {
;     ...
;                 const float mn = fmaxf(m_run, cm), sc = exp2f(m_run - mn);
;                 float ls = 0.f;
; #pragma unroll
;                 for (int r = 0; r < 8; ++r) { pv[r] = exp2f(pv[r] - mn); ls += pv[r]; }
;                 ls += __shfl_xor(ls, 16); ls += __shfl_xor(ls, 32);
;                 l_run = l_run * sc + ls; m_run = mn;
; #pragma unroll
;                 for (int dt = 0; dt < DT; ++dt) oacc[dt] = oacc[dt] * sc;
;             }
;             bf16x8 pb; { v4u t; t.x = pk2(pv[0], pv[1]); t.y = pk2(pv[2], pv[3]); t.z = pk2(pv[4], pv[5]); t.w = pk2(pv[6], pv[7]); pb = __builtin_bit_cast(bf16x8, t); }
;             if constexpr (USE_TR) {
; #pragma unroll
;                 for (int d4 = 0; d4 < DT; d4 += 4) { bf16x8 vf4[4]; read_vfrags4_trp<P>(vl + 16 * d4, i, g, vf4);
; #pragma unroll
;                     for (int dt = 0; dt < 4; ++dt) oacc[d4 + dt] = __builtin_amdgcn_mfma_f32_16x16x32_bf16(vf4[dt], pb, oacc[d4 + dt], 0, 0, 0); }
	v_add_f32_e32 v70, v70, v141
	ds_bpermute_b32 v141, v97, v70
	v_pk_mul_f32 v[10:11], v[10:11], v[156:157] op_sel_hi:[1,0]
	v_pk_mul_f32 v[8:9], v[8:9], v[156:157] op_sel_hi:[1,0]
	v_pk_mul_f32 v[14:15], v[14:15], v[156:157] op_sel_hi:[1,0]
	v_pk_mul_f32 v[12:13], v[12:13], v[156:157] op_sel_hi:[1,0]
	s_waitcnt lgkmcnt(0)
	v_add_f32_e32 v70, v70, v141
	v_fmac_f32_e32 v70, v172, v156
	v_cvt_pk_bf16_f32 v156, v157, v163
	v_cvt_pk_bf16_f32 v157, v158, v159
	v_cvt_pk_bf16_f32 v158, v160, v161
	v_cvt_pk_bf16_f32 v159, v162, v164
	ds_read_b64_tr_b16 v[172:173], v98
	ds_read_b64_tr_b16 v[168:169], v98 offset:32
	ds_read_b64_tr_b16 v[164:165], v98 offset:64
	ds_read_b64_tr_b16 v[160:161], v98 offset:96
	ds_read_b64_tr_b16 v[174:175], v99
	ds_read_b64_tr_b16 v[170:171], v99 offset:32
	ds_read_b64_tr_b16 v[166:167], v99 offset:64
	ds_read_b64_tr_b16 v[162:163], v99 offset:96
	s_waitcnt lgkmcnt(0)
	v_mfma_f32_16x16x32_bf16 v[0:3], v[172:175], v[156:159], v[0:3]
	v_mfma_f32_16x16x32_bf16 v[4:7], v[168:171], v[156:159], v[4:7]
	v_mfma_f32_16x16x32_bf16 v[8:11], v[164:167], v[156:159], v[8:11]
	v_mfma_f32_16x16x32_bf16 v[12:15], v[160:163], v[156:159], v[12:15]
	s_cbranch_scc1 .LBB0_323
	s_waitcnt vmcnt(7)
	v_mfma_f32_16x16x32_bf16 v[28:31], v[28:31], v[16:19], 0
	s_waitcnt vmcnt(3)
	ds_write_b128 v122, v[40:43]
	s_waitcnt vmcnt(2)
	ds_write_b128 v123, v[44:47]
	s_waitcnt vmcnt(1)
	ds_write_b128 v124, v[48:51]
	s_waitcnt vmcnt(0)
	ds_write_b128 v125, v[52:55]
	s_movk_i32 s0, 0x110
	v_mfma_f32_16x16x32_bf16 v[16:19], v[36:39], v[16:19], 0
	v_mfma_f32_16x16x32_bf16 v[24:27], v[24:27], v[20:23], v[28:31]
	v_mfma_f32_16x16x32_bf16 v[16:19], v[32:35], v[20:23], v[16:19]
	v_add_u32_e32 v20, s18, v133
	v_cmp_gt_u32_e32 vcc, s84, v20
	s_nop 4
	v_fma_f32 v20, v24, s76, -v134
	s_and_b64 vcc, s[38:39], vcc
	v_mul_f32_e32 v20, 0x3fb8aa3b, v20
	v_cndmask_b32_e32 v21, v188, v20, vcc
	v_add_u32_e32 v20, s18, v135
	v_cmp_gt_u32_e32 vcc, s84, v20
	v_fma_f32 v20, v25, s76, -v139
	s_and_b64 vcc, s[40:41], vcc
	v_mul_f32_e32 v20, 0x3fb8aa3b, v20
	v_cndmask_b32_e32 v22, v188, v20, vcc
	v_add_u32_e32 v20, s18, v142
	v_cmp_gt_u32_e32 vcc, s84, v20
	v_fma_f32 v20, v26, s76, -v143
	s_and_b64 vcc, s[42:43], vcc
	v_mul_f32_e32 v20, 0x3fb8aa3b, v20
	v_cndmask_b32_e32 v23, v188, v20, vcc
	v_add_u32_e32 v20, s18, v144
	v_cmp_gt_u32_e32 vcc, s84, v20
	v_fma_f32 v20, v27, s76, -v145
	s_and_b64 vcc, s[44:45], vcc
	v_mul_f32_e32 v20, 0x3fb8aa3b, v20
	v_cndmask_b32_e32 v24, v188, v20, vcc
	v_add_u32_e32 v20, s18, v146
	v_cmp_gt_u32_e32 vcc, s84, v20
	v_fma_f32 v16, v16, s76, -v147
	s_and_b64 vcc, s[46:47], vcc
	v_mul_f32_e32 v16, 0x3fb8aa3b, v16
	v_add_u32_e32 v20, s18, v148
	v_cndmask_b32_e32 v16, v188, v16, vcc
	v_cmp_gt_u32_e32 vcc, s84, v20
	v_fma_f32 v17, v17, s76, -v149
	s_and_b64 vcc, s[48:49], vcc
	v_mul_f32_e32 v17, 0x3fb8aa3b, v17
	v_add_u32_e32 v20, s18, v150
	v_cndmask_b32_e32 v17, v188, v17, vcc
	v_cmp_gt_u32_e32 vcc, s84, v20
	v_fma_f32 v18, v18, s76, -v151
	s_and_b64 vcc, s[50:51], vcc
	v_mul_f32_e32 v18, 0x3fb8aa3b, v18
	v_add_u32_e32 v20, s18, v152
	v_cndmask_b32_e32 v18, v188, v18, vcc
	v_cmp_gt_u32_e32 vcc, s84, v20
	v_fma_f32 v19, v19, s76, -v153
	v_max_f32_e32 v20, v21, v22
	s_and_b64 vcc, s[52:53], vcc
	v_mul_f32_e32 v19, 0x3fb8aa3b, v19
	v_max3_f32 v20, v20, v23, v24
	v_cndmask_b32_e32 v19, v188, v19, vcc
	v_max3_f32 v20, v20, v16, v17
	v_max3_f32 v20, v20, v18, v19
	ds_bpermute_b32 v25, v96, v20
	s_waitcnt lgkmcnt(0)
	v_max_f32_e32 v25, v25, v25
	v_max_f32_e32 v20, v20, v25
	ds_bpermute_b32 v25, v97, v20
	s_waitcnt lgkmcnt(0)
	v_max3_f32 v20, v136, v20, v25
	v_sub_f32_e32 v21, v21, v20
	v_sub_f32_e32 v23, v23, v20
	v_sub_f32_e32 v24, v24, v20
	v_exp_f32_e32 v21, v21
	v_sub_f32_e32 v16, v16, v20
	v_sub_f32_e32 v17, v17, v20
	v_mov_b32_e32 v26, v21
	v_sub_f32_e32 v21, v22, v20
	v_sub_f32_e32 v18, v18, v20
	v_sub_f32_e32 v19, v19, v20
	v_exp_f32_e32 v21, v21
	v_sub_f32_e32 v25, v136, v20
	v_exp_f32_e32 v23, v23
	v_mov_b32_e32 v22, v21
	v_exp_f32_e32 v24, v24
	v_add_f32_e32 v21, v26, v22
	v_exp_f32_e32 v16, v16
	v_add_f32_e32 v21, v23, v21
	v_add_f32_e32 v21, v24, v21
	v_mov_b32_e32 v27, v16
	v_add_f32_e32 v16, v27, v21
	v_bfe_u32 v28, v24, 16, 1
	v_exp_f32_e32 v17, v17
	v_bfe_u32 v29, v22, 16, 1
	v_exp_f32_e32 v18, v18
	v_add_f32_e32 v16, v17, v16
	v_exp_f32_e32 v19, v19
	v_add_f32_e32 v16, v18, v16
	v_add_f32_e32 v21, v19, v16
	v_mov_b32_e32 v16, v25
	v_exp_f32_e32 v16, v16
	v_add3_u32 v22, v22, v29, s86
	v_add3_u32 v24, v24, v28, s86
	ds_bpermute_b32 v25, v96, v21
	v_pk_mul_f32 v[2:3], v[2:3], v[16:17] op_sel_hi:[1,0]
	v_pk_mul_f32 v[0:1], v[0:1], v[16:17] op_sel_hi:[1,0]
	v_pk_mul_f32 v[6:7], v[6:7], v[16:17] op_sel_hi:[1,0]
	v_pk_mul_f32 v[4:5], v[4:5], v[16:17] op_sel_hi:[1,0]
	s_waitcnt lgkmcnt(0)
	v_add_f32_e32 v21, v21, v25
	ds_bpermute_b32 v25, v97, v21
	v_pk_mul_f32 v[10:11], v[10:11], v[16:17] op_sel_hi:[1,0]
	v_pk_mul_f32 v[8:9], v[8:9], v[16:17] op_sel_hi:[1,0]
	v_pk_mul_f32 v[14:15], v[14:15], v[16:17] op_sel_hi:[1,0]
	v_pk_mul_f32 v[12:13], v[12:13], v[16:17] op_sel_hi:[1,0]
	s_waitcnt lgkmcnt(0)
	v_add_f32_e32 v21, v21, v25
	v_fmac_f32_e32 v21, v70, v16
	v_bfe_u32 v16, v19, 16, 1
	v_bfe_u32 v25, v17, 16, 1
	v_add3_u32 v17, v17, v25, s86
	v_add3_u32 v16, v19, v16, s86
	v_bfe_u32 v19, v26, 16, 1
	v_bfe_u32 v25, v23, 16, 1
	v_bfe_u32 v28, v27, 16, 1
	v_bfe_u32 v29, v18, 16, 1
	v_add3_u32 v18, v18, v29, s86
	v_add3_u32 v27, v27, v28, s86
	v_add3_u32 v23, v23, v25, s86
	v_add3_u32 v19, v26, v19, s86
	v_lshrrev_b32_e32 v25, 16, v19
	v_lshrrev_b32_e32 v23, 16, v23
	v_lshrrev_b32_e32 v26, 16, v27
	v_lshrrev_b32_e32 v18, 16, v18
	v_and_or_b32 v19, v16, s85, v18
	v_and_or_b32 v18, v17, s85, v26
	v_and_or_b32 v17, v24, s85, v23
	v_and_or_b32 v16, v22, s85, v25
	ds_read_b64_tr_b16 v[34:35], v98
	ds_read_b64_tr_b16 v[30:31], v98 offset:32
	ds_read_b64_tr_b16 v[26:27], v98 offset:64
	ds_read_b64_tr_b16 v[22:23], v98 offset:96
	ds_read_b64_tr_b16 v[36:37], v99
	ds_read_b64_tr_b16 v[32:33], v99 offset:32
	ds_read_b64_tr_b16 v[28:29], v99 offset:64
	ds_read_b64_tr_b16 v[24:25], v99 offset:96
	s_waitcnt lgkmcnt(0)
	s_andn2_b64 vcc, exec, s[4:5]
	v_bfi_b32 v36, s87, v36, v36
	v_bfi_b32 v32, s87, v32, v32
	v_bfi_b32 v28, s87, v28, v28
	v_bfi_b32 v24, s87, v24, v24
	v_mfma_f32_16x16x32_bf16 v[0:3], v[34:37], v[16:19], v[0:3]
	v_mfma_f32_16x16x32_bf16 v[4:7], v[30:33], v[16:19], v[4:7]
	v_mfma_f32_16x16x32_bf16 v[8:11], v[26:29], v[16:19], v[8:11]
	v_subrev_u32_e32 v29, s13, v155
	v_mfma_f32_16x16x32_bf16 v[12:15], v[22:25], v[16:19], v[12:15]
	v_mul_lo_u32 v16, v29, s0
	v_add_u32_e32 v42, v116, v16
	s_cbranch_vccnz .LBB0_327
; #define LAS __attribute__((address_space(3)))
; __device__ __forceinline__ void mixer_phase(const Ctx& C, const bf16* PROJ, bf16* MIX, const float* decay_logit  , const float* ret_gain, const float* att_gain) {
;     ...
;                 const int row = tb + i * d - T0;
;                 LAS float* orow = OL + row * 68 + 4 * g;
;                 if (pat > 0) {
;                     const float m0 = ML[row * 2], l0 = ML[row * 2 + 1];
;                     const float mn = fmaxf(m0, m), a = exp2f(m0 - mn), bb = exp2f(m - mn);
; #pragma unroll
;                     for (int dt = 0; dt < 4; ++dt) { const f32x4 p0 = *(LAS f32x4*)(orow + 16 * dt); o[dt] = p0 * a + o[dt] * bb; }
;                     l = l0 * a + l * bb; m = mn;
	v_lshl_add_u32 v16, v29, 3, 0
	v_add_u32_e32 v16, 0x1a000, v16
	ds_read_b64 v[18:19], v16
	ds_read_b128 v[22:25], v42 offset:36864
	v_max_f32_e32 v17, v20, v20
	s_waitcnt lgkmcnt(1)
	v_max_f32_e32 v16, v18, v18
	v_max_f32_e32 v16, v16, v17
	v_sub_f32_e32 v17, v18, v16
	s_nop 1
	v_exp_f32_e32 v17, v17
	s_nop 0
	v_mov_b32_e32 v18, v17
	v_sub_f32_e32 v17, v20, v16
	s_waitcnt lgkmcnt(0)
	v_pk_mul_f32 v[22:23], v[22:23], v[18:19] op_sel_hi:[1,0]
	v_pk_mul_f32 v[24:25], v[24:25], v[18:19] op_sel_hi:[1,0]
	v_exp_f32_e32 v17, v17
	s_and_b64 vcc, exec, s[6:7]
	v_mov_b32_e32 v26, v17
	v_pk_fma_f32 v[2:3], v[2:3], v[26:27], v[24:25] op_sel_hi:[1,0,1]
	v_pk_fma_f32 v[0:1], v[0:1], v[26:27], v[22:23] op_sel_hi:[1,0,1]
	ds_read_b128 v[22:25], v42 offset:36928
	v_mov_b32_e32 v20, v19
	s_waitcnt lgkmcnt(0)
	v_pk_mul_f32 v[22:23], v[22:23], v[18:19] op_sel_hi:[1,0]
	v_pk_mul_f32 v[24:25], v[24:25], v[18:19] op_sel_hi:[1,0]
	v_pk_fma_f32 v[4:5], v[4:5], v[26:27], v[22:23] op_sel_hi:[1,0,1]
	v_pk_fma_f32 v[6:7], v[6:7], v[26:27], v[24:25] op_sel_hi:[1,0,1]
	ds_read_b128 v[22:25], v42 offset:36992
	s_waitcnt lgkmcnt(0)
	v_pk_mul_f32 v[22:23], v[18:19], v[22:23] op_sel_hi:[0,1]
	v_pk_mul_f32 v[24:25], v[18:19], v[24:25] op_sel_hi:[0,1]
	v_pk_fma_f32 v[10:11], v[10:11], v[26:27], v[24:25] op_sel_hi:[1,0,1]
	v_pk_fma_f32 v[8:9], v[8:9], v[26:27], v[22:23] op_sel_hi:[1,0,1]
	ds_read_b128 v[22:25], v42 offset:37056
	s_waitcnt lgkmcnt(0)
	v_pk_mul_f32 v[22:23], v[18:19], v[22:23] op_sel_hi:[0,1]
	v_pk_mul_f32 v[24:25], v[18:19], v[24:25] op_sel_hi:[0,1]
	v_pk_fma_f32 v[12:13], v[12:13], v[26:27], v[22:23] op_sel_hi:[1,0,1]
	v_mov_b32_e32 v19, v26
	v_mul_f32_e32 v22, v21, v26
	v_pk_fma_f32 v[14:15], v[14:15], v[26:27], v[24:25] op_sel_hi:[1,0,1]
	v_pk_fma_f32 v[18:19], v[20:21], v[18:19], v[22:23] op_sel_hi:[1,1,0]
	s_cbranch_vccz .LBB0_328
	v_mov_b32_e32 v17, v18
	s_mov_b64 s[10:11], -1
	v_mov_b64_e32 v[20:21], v[16:17]
	s_cbranch_execz .LBB0_329
	s_branch .LBB0_330
